# v65 + SSD transpose step: B-row LDS reads issued ahead of the 2-byte transpose stores (all three chunk loops)
# speedup vs baseline: 1.0139x; 1.0033x over previous
; DI float bflo(unsigned u) { return __uint_as_float(u << 16); }
; DI float bfhi(unsigned u) { return __uint_as_float(u & 0xffff0000u); }
; template <int PROBE, int SONLY, int CPS>
; DI void ssd_chunk_loop(const Params& p, int layer, int b, int e, int c0, f32x4 (&h)[8], float& dtot, bool write_final) {
;     ...
;     {
;       const int nb_ = b * 2048 + ((cc + 1 < c0 + CPS) ? (cc + 1) : cc) * 64;
; #pragma unroll
;       for (int i = 0; i < 4; ++i) {
;         const int idx = tid + 256 * i, r = idx >> 4, c16 = idx & 15;
;         if (!SONLY) pc[i] = *(const u32x4*)(XBC + (size_t)(nb_ + r) * 1280 + 1024 + g * 128 + c16 * 8);
;         pb[i] = *(const u32x4*)(XBC + (size_t)(nb_ + r) * 1280 + 768 + g * 128 + c16 * 8);
;       }
; #pragma unroll
;       for (int i = 0; i < 2; ++i) {
;         const int idx = tid + 256 * i, r = idx >> 3, c8 = idx & 7;
;         px[i] = *(const u32x4*)(XBC + (size_t)(nb_ + r) * 1280 + e * 64 + c8 * 8);
;       }
;       pru = PROJ[(size_t)(nb_ + lane) * NPAD + C_DT + e];
;     }
;     uint2 dx[4], dz[4];
;     if (!SONLY)
; #pragma unroll
;     for (int qt = 0; qt < 4; ++qt) {
;       const size_t row = (size_t)(base + qt * 16 + l15);
;       const int pcol = w * 16 + quad * 4;
;       dx[qt] = *(const uint2*)(XBC + row * 1280 + e * 64 + pcol);
;       dz[qt] = *(const uint2*)(PROJ + row * NPAD + C_Z + e * 64 + pcol);
;     }
;     __syncthreads();
;     dtot += acs_s[63];
;     if (!(PROBE & 2)) {
; #pragma unroll
;     for (int i = 0; i < 2; ++i) {
;       const int idx = tid + 256 * i, r = idx >> 3, c8 = idx & 7;
;       const float dtv = dt_s[r];
;       float f[8]; unpack8v(xr[i], f);
; #pragma unroll
;       for (int j = 0; j < 8; ++j) Xt[(c8 * 8 + j) * 72 + r] = f2bf(f[j] * dtv);
;     }
;     {
;       const int q = tid & 63, ng = tid >> 6;
;       const float dte = __expf(acs_s[63] - acs_s[q]);
; #pragma unroll
;       for (int i = 0; i < 8; ++i) {
;         const uint2 v = *(const uint2*)(Bs + q * 136 + ng * 32 + i * 4);
;         Bt2[(ng * 32 + i * 4 + 0) * 72 + q] = f2bf(bflo(v.x) * dte);
;         Bt2[(ng * 32 + i * 4 + 1) * 72 + q] = f2bf(bfhi(v.x) * dte);
;         Bt2[(ng * 32 + i * 4 + 2) * 72 + q] = f2bf(bflo(v.y) * dte);
;         Bt2[(ng * 32 + i * 4 + 3) * 72 + q] = f2bf(bfhi(v.y) * dte);
;       }
;     }
.LBB0_483:
	s_or_b64 exec, exec, s[50:51]
	s_add_i32 s0, s6, s7
	s_add_i32 s1, s0, 1
	s_cmp_lt_i32 s1, s18
	s_cselect_b32 s0, s1, s0
	s_lshl_b32 s0, s0, 6
	s_add_i32 s22, s0, s13
	s_waitcnt vmcnt(0)
	v_or_b32_e32 v95, s22, v72
	v_mov_b64_e32 v[96:97], s[4:5]
	v_add_u32_e32 v0, s22, v73
	v_add_u32_e32 v4, s22, v75
	v_add_u32_e32 v8, s22, v76
	v_add_u32_e32 v12, s22, v77
	v_add_u32_e32 v16, s22, v74
	v_add_u32_e32 v20, s22, v78
	v_mad_i64_i32 v[96:97], s[0:1], v95, s97, v[96:97]
	v_mad_i64_i32 v[0:1], s[0:1], v0, s34, v[70:71]
	v_mad_i64_i32 v[4:5], s[0:1], v4, s34, v[70:71]
	v_mad_i64_i32 v[8:9], s[0:1], v8, s34, v[70:71]
	v_mad_i64_i32 v[12:13], s[0:1], v12, s34, v[70:71]
	v_mad_i64_i32 v[16:17], s[0:1], v16, s34, v[66:67]
	v_mad_i64_i32 v[20:21], s[0:1], v20, s34, v[66:67]
	v_lshl_add_u64 v[96:97], v[64:65], 1, v[96:97]
	v_add_co_u32_e64 v96, s[0:1], s16, v96
	global_load_dwordx4 v[0:3], v[0:1], off offset:1536
	s_nop 0
	v_addc_co_u32_e64 v97, s[0:1], 0, v97, s[0:1]
	global_load_dwordx4 v[4:7], v[4:5], off offset:1536
	v_lshlrev_b32_e32 v99, 16, v28
	global_load_dwordx4 v[8:11], v[8:9], off offset:1536
	v_and_b32_e32 v28, 0xffff0000, v28
	global_load_dwordx4 v[12:15], v[12:13], off offset:1536
	v_lshlrev_b32_e32 v100, 16, v29
	global_load_dwordx4 v[16:19], v[16:17], off
	v_and_b32_e32 v29, 0xffff0000, v29
	global_load_dwordx4 v[20:23], v[20:21], off
	v_lshlrev_b32_e32 v101, 16, v30
	global_load_ushort v95, v[96:97], off offset:1536
	s_waitcnt lgkmcnt(0)
	s_barrier
	ds_read_b32 v98, v82
	ds_read_b32 v224, v81
	ds_read_b64 v[228:229], v93 offset:17408
	ds_read_b64 v[232:233], v93 offset:17416
	ds_read_b64 v[236:237], v93 offset:17424
	ds_read_b64 v[240:241], v93 offset:17432
	ds_read_b64 v[244:245], v93 offset:17440
	ds_read_b64 v[248:249], v93 offset:17448
	v_and_b32_e32 v30, 0xffff0000, v30
	v_lshlrev_b32_e32 v102, 16, v31
	v_and_b32_e32 v31, 0xffff0000, v31
	v_mov_b32_e32 v96, s20
	s_nop 0
	s_waitcnt lgkmcnt(7)
	v_mul_f32_e32 v28, v98, v28
	v_cvt_pk_bf16_f32 v28, v28, s0
	ds_write_b16 v91, v28 offset:53392
	v_mul_f32_e32 v28, v98, v100
	v_cvt_pk_bf16_f32 v28, v28, s0
	ds_write_b16 v91, v28 offset:53536
	v_mul_f32_e32 v28, v98, v29
	v_cvt_pk_bf16_f32 v28, v28, s0
	ds_write_b16 v91, v28 offset:53680
	v_mul_f32_e32 v28, v98, v101
	v_cvt_pk_bf16_f32 v28, v28, s0
	ds_write_b16 v91, v28 offset:53824
	v_mul_f32_e32 v28, v98, v30
	v_cvt_pk_bf16_f32 v28, v28, s0
	ds_write_b16 v91, v28 offset:53968
	v_mul_f32_e32 v28, v98, v102
	v_cvt_pk_bf16_f32 v28, v28, s0
	ds_write_b16 v91, v28 offset:54112
	v_mul_f32_e32 v28, v98, v31
	v_cvt_pk_bf16_f32 v28, v28, s0
	ds_write_b16 v91, v28 offset:54256
	ds_read_b32 v28, v83
	v_lshlrev_b32_e32 v29, 16, v24
	v_and_b32_e32 v24, 0xffff0000, v24
	v_mul_f32_e32 v99, v98, v99
	v_cvt_pk_bf16_f32 v99, v99, s0
	s_nop 0
	s_waitcnt lgkmcnt(0)
	v_mul_f32_e32 v24, v28, v24
	v_lshlrev_b32_e32 v30, 16, v25
	v_cvt_pk_bf16_f32 v24, v24, s0
	ds_write_b16 v91, v99 offset:53248
	ds_write_b16 v92, v24 offset:53392
	v_mul_f32_e32 v24, v28, v30
	v_and_b32_e32 v25, 0xffff0000, v25
	v_cvt_pk_bf16_f32 v24, v24, s0
	ds_write_b16 v92, v24 offset:53536
	v_mul_f32_e32 v24, v28, v25
	v_lshlrev_b32_e32 v31, 16, v26
	v_cvt_pk_bf16_f32 v24, v24, s0
	ds_write_b16 v92, v24 offset:53680
	v_mul_f32_e32 v24, v28, v31
	v_and_b32_e32 v26, 0xffff0000, v26
	v_cvt_pk_bf16_f32 v24, v24, s0
	ds_write_b16 v92, v24 offset:53824
	v_mul_f32_e32 v24, v28, v26
	v_lshlrev_b32_e32 v98, 16, v27
	v_cvt_pk_bf16_f32 v24, v24, s0
	ds_write_b16 v92, v24 offset:53968
	v_mul_f32_e32 v24, v28, v98
	v_and_b32_e32 v27, 0xffff0000, v27
	v_cvt_pk_bf16_f32 v24, v24, s0
	ds_write_b16 v92, v24 offset:54112
	v_mul_f32_e32 v24, v28, v27
	v_cvt_pk_bf16_f32 v24, v24, s0
	ds_read_b32 v97, v96
	ds_write_b16 v92, v24 offset:54256
	s_nop 0
	v_mul_f32_e32 v29, v28, v29
	v_cvt_pk_bf16_f32 v29, v29, s0
	ds_write_b16 v92, v29 offset:53248
	s_nop 0
	s_waitcnt lgkmcnt(2)
	v_add_f32_e32 v86, v86, v97
	s_nop 0
	v_sub_f32_e32 v24, v97, v224
	ds_read_b64 v[224:225], v93 offset:17456
	v_mul_f32_e32 v24, 0x3fb8aa3b, v24
	v_exp_f32_e32 v26, v24
	s_nop 0
	s_add_i32 s7, s7, 1
	s_cmp_lg_u32 s7, 10
	s_nop 0
	v_lshlrev_b32_e32 v27, 16, v228
	v_and_b32_e32 v24, 0xffff0000, v228
	v_mul_f32_e32 v27, v26, v27
	v_mul_f32_e32 v24, v26, v24
	v_cvt_pk_bf16_f32 v27, v27, s0
	v_cvt_pk_bf16_f32 v24, v24, s0
	ds_write_b16 v84, v27 offset:34816
	ds_write_b16 v85, v24 offset:34960
	v_lshlrev_b32_e32 v24, 16, v229
	v_mul_f32_e32 v24, v26, v24
	v_cvt_pk_bf16_f32 v24, v24, s0
	ds_write_b16 v85, v24 offset:35104
	v_and_b32_e32 v24, 0xffff0000, v229
	v_mul_f32_e32 v24, v26, v24
	v_cvt_pk_bf16_f32 v24, v24, s0
	ds_write_b16 v85, v24 offset:35248
	s_nop 0
	s_nop 0
	v_lshlrev_b32_e32 v27, 16, v232
	v_and_b32_e32 v24, 0xffff0000, v232
	v_mul_f32_e32 v27, v26, v27
	v_mul_f32_e32 v24, v26, v24
	v_cvt_pk_bf16_f32 v27, v27, s0
	v_cvt_pk_bf16_f32 v24, v24, s0
	ds_write_b16 v84, v27 offset:35392
	ds_write_b16 v85, v24 offset:35536
	v_lshlrev_b32_e32 v24, 16, v233
	v_mul_f32_e32 v24, v26, v24
	v_cvt_pk_bf16_f32 v24, v24, s0
	ds_write_b16 v85, v24 offset:35680
	v_and_b32_e32 v24, 0xffff0000, v233
	v_mul_f32_e32 v24, v26, v24
	v_cvt_pk_bf16_f32 v24, v24, s0
	ds_write_b16 v85, v24 offset:35824
	s_nop 0
	s_nop 0
	v_lshlrev_b32_e32 v27, 16, v236
	v_and_b32_e32 v24, 0xffff0000, v236
	v_mul_f32_e32 v27, v26, v27
	v_mul_f32_e32 v24, v26, v24
	v_cvt_pk_bf16_f32 v27, v27, s0
	v_cvt_pk_bf16_f32 v24, v24, s0
	ds_write_b16 v84, v27 offset:35968
	ds_write_b16 v85, v24 offset:36112
	v_lshlrev_b32_e32 v24, 16, v237
	v_mul_f32_e32 v24, v26, v24
	v_cvt_pk_bf16_f32 v24, v24, s0
	ds_write_b16 v85, v24 offset:36256
	v_and_b32_e32 v24, 0xffff0000, v237
; DI float bflo(unsigned u) { return __uint_as_float(u << 16); }
; DI float bfhi(unsigned u) { return __uint_as_float(u & 0xffff0000u); }
; DI f32x4 mfma16(bf16x8 a, bf16x8 b, f32x4 c) { return __builtin_amdgcn_mfma_f32_16x16x32_bf16(a, b, c, 0, 0, 0); }
; template <int PROBE, int SONLY, int CPS>
; DI void ssd_chunk_loop(const Params& p, int layer, int b, int e, int c0, f32x4 (&h)[8], float& dtot, bool write_final) {
;     ...
;     {
;       const int q = tid & 63, ng = tid >> 6;
;       const float dte = __expf(acs_s[63] - acs_s[q]);
; #pragma unroll
;       for (int i = 0; i < 8; ++i) {
;         const uint2 v = *(const uint2*)(Bs + q * 136 + ng * 32 + i * 4);
;         Bt2[(ng * 32 + i * 4 + 0) * 72 + q] = f2bf(bflo(v.x) * dte);
;         Bt2[(ng * 32 + i * 4 + 1) * 72 + q] = f2bf(bfhi(v.x) * dte);
;         Bt2[(ng * 32 + i * 4 + 2) * 72 + q] = f2bf(bflo(v.y) * dte);
;         Bt2[(ng * 32 + i * 4 + 3) * 72 + q] = f2bf(bfhi(v.y) * dte);
;       }
;     }
;     ...
;     if (!(PROBE & 8)) {
;       const float cd = __expf(acs_s[63]);
; #pragma unroll
;       for (int nt = 0; nt < 8; ++nt) h[nt] *= cd;
; #pragma unroll
;       for (int ks = 0; ks < 2; ++ks) {
;         const bf16x8 xf = ldfrag(Xt, 72, w * 16, ks * 32, lane);
; #pragma unroll
;         for (int nt = 0; nt < 8; ++nt) h[nt] = mfma16(ldfrag(Bt2, 72, nt * 16, ks * 32, lane), xf, h[nt]);
;       }
	v_mul_f32_e32 v24, v26, v24
	v_cvt_pk_bf16_f32 v24, v24, s0
	ds_write_b16 v85, v24 offset:36400
	s_nop 0
	s_nop 0
	v_lshlrev_b32_e32 v27, 16, v240
	v_and_b32_e32 v24, 0xffff0000, v240
	v_mul_f32_e32 v27, v26, v27
	v_mul_f32_e32 v24, v26, v24
	v_cvt_pk_bf16_f32 v27, v27, s0
	v_cvt_pk_bf16_f32 v24, v24, s0
	ds_write_b16 v84, v27 offset:36544
	ds_write_b16 v85, v24 offset:36688
	v_lshlrev_b32_e32 v24, 16, v241
	v_mul_f32_e32 v24, v26, v24
	v_cvt_pk_bf16_f32 v24, v24, s0
	ds_write_b16 v85, v24 offset:36832
	v_and_b32_e32 v24, 0xffff0000, v241
	v_mul_f32_e32 v24, v26, v24
	v_cvt_pk_bf16_f32 v24, v24, s0
	ds_write_b16 v85, v24 offset:36976
	s_nop 0
	s_nop 0
	v_lshlrev_b32_e32 v27, 16, v244
	v_and_b32_e32 v24, 0xffff0000, v244
	v_mul_f32_e32 v27, v26, v27
	v_mul_f32_e32 v24, v26, v24
	v_cvt_pk_bf16_f32 v27, v27, s0
	v_cvt_pk_bf16_f32 v24, v24, s0
	ds_write_b16 v84, v27 offset:37120
	ds_write_b16 v85, v24 offset:37264
	v_lshlrev_b32_e32 v24, 16, v245
	v_mul_f32_e32 v24, v26, v24
	v_cvt_pk_bf16_f32 v24, v24, s0
	ds_write_b16 v85, v24 offset:37408
	v_and_b32_e32 v24, 0xffff0000, v245
	v_mul_f32_e32 v24, v26, v24
	v_cvt_pk_bf16_f32 v24, v24, s0
	ds_write_b16 v85, v24 offset:37552
	s_nop 0
	s_nop 0
	v_lshlrev_b32_e32 v27, 16, v248
	v_and_b32_e32 v24, 0xffff0000, v248
	v_mul_f32_e32 v27, v26, v27
	v_mul_f32_e32 v24, v26, v24
	v_cvt_pk_bf16_f32 v27, v27, s0
	v_cvt_pk_bf16_f32 v24, v24, s0
	ds_write_b16 v84, v27 offset:37696
	ds_write_b16 v85, v24 offset:37840
	v_lshlrev_b32_e32 v24, 16, v249
	v_mul_f32_e32 v24, v26, v24
	v_cvt_pk_bf16_f32 v24, v24, s0
	ds_write_b16 v85, v24 offset:37984
	v_and_b32_e32 v24, 0xffff0000, v249
	v_mul_f32_e32 v24, v26, v24
	v_cvt_pk_bf16_f32 v24, v24, s0
	ds_write_b16 v85, v24 offset:38128
	s_nop 0
	s_nop 0
	s_waitcnt lgkmcnt(15)
	v_lshlrev_b32_e32 v27, 16, v224
	v_and_b32_e32 v24, 0xffff0000, v224
	v_mul_f32_e32 v27, v26, v27
	v_mul_f32_e32 v24, v26, v24
	v_cvt_pk_bf16_f32 v27, v27, s0
	v_cvt_pk_bf16_f32 v24, v24, s0
	ds_write_b16 v84, v27 offset:38272
	ds_write_b16 v85, v24 offset:38416
	v_lshlrev_b32_e32 v24, 16, v225
	v_mul_f32_e32 v24, v26, v24
	v_cvt_pk_bf16_f32 v24, v24, s0
	ds_write_b16 v85, v24 offset:38560
	v_and_b32_e32 v24, 0xffff0000, v225
	v_mul_f32_e32 v24, v26, v24
	v_cvt_pk_bf16_f32 v24, v24, s0
	ds_write_b16 v85, v24 offset:38704
	ds_read_b64 v[24:25], v93 offset:17464
	s_nop 0
	s_waitcnt lgkmcnt(0)
	v_lshlrev_b32_e32 v27, 16, v24
	v_and_b32_e32 v24, 0xffff0000, v24
	v_mul_f32_e32 v27, v26, v27
	v_mul_f32_e32 v24, v26, v24
	v_cvt_pk_bf16_f32 v27, v27, s0
	v_cvt_pk_bf16_f32 v24, v24, s0
	ds_write_b16 v84, v27 offset:38848
	ds_write_b16 v85, v24 offset:38992
	v_lshlrev_b32_e32 v24, 16, v25
	v_mul_f32_e32 v24, v26, v24
	v_cvt_pk_bf16_f32 v24, v24, s0
	ds_write_b16 v85, v24 offset:39136
	v_and_b32_e32 v24, 0xffff0000, v25
	v_mul_f32_e32 v24, v26, v24
	v_cvt_pk_bf16_f32 v24, v24, s0
	ds_write_b16 v85, v24 offset:39280
	s_waitcnt lgkmcnt(0)
	s_waitcnt lgkmcnt(0)
	s_barrier
	ds_read_b32 v24, v96
	ds_read_b128 v[224:227], v68 offset:53248
	ds_read_b128 v[228:231], v94 offset:34816
	ds_read_b128 v[232:235], v94 offset:37120
	ds_read_b128 v[236:239], v94 offset:39424
	ds_read_b128 v[240:243], v94 offset:41728
	ds_read_b128 v[244:247], v94 offset:44032
	ds_read_b128 v[248:251], v94 offset:46336
	s_nop 0
	s_waitcnt lgkmcnt(7)
	v_mul_f32_e32 v24, 0x3fb8aa3b, v24
	v_exp_f32_e32 v96, v24
	s_nop 0
	v_pk_mul_f32 v[26:27], v[62:63], v[96:97] op_sel_hi:[1,0]
	v_pk_mul_f32 v[24:25], v[60:61], v[96:97] op_sel_hi:[1,0]
	v_pk_mul_f32 v[30:31], v[58:59], v[96:97] op_sel_hi:[1,0]
	v_pk_mul_f32 v[28:29], v[56:57], v[96:97] op_sel_hi:[1,0]
	s_nop 0
	s_nop 0
	s_nop 0
	s_waitcnt lgkmcnt(5)
	v_mfma_f32_16x16x32_bf16 v[24:27], v[228:231], v[224:227], v[24:27]
	ds_read_b128 v[228:231], v94 offset:48640
	s_nop 0
	v_pk_mul_f32 v[54:55], v[54:55], v[96:97] op_sel_hi:[1,0]
	v_pk_mul_f32 v[52:53], v[52:53], v[96:97] op_sel_hi:[1,0]
	s_nop 0
	s_waitcnt lgkmcnt(5)
	v_mfma_f32_16x16x32_bf16 v[28:31], v[232:235], v[224:227], v[28:31]
	ds_read_b128 v[232:235], v94 offset:50944
	s_nop 0
	v_pk_mul_f32 v[50:51], v[50:51], v[96:97] op_sel_hi:[1,0]
	v_pk_mul_f32 v[48:49], v[48:49], v[96:97] op_sel_hi:[1,0]
	s_nop 0
	s_waitcnt lgkmcnt(5)
	v_mfma_f32_16x16x32_bf16 v[52:55], v[236:239], v[224:227], v[52:55]
	ds_read_b128 v[236:239], v94 offset:34880
	s_nop 0
	v_pk_mul_f32 v[46:47], v[46:47], v[96:97] op_sel_hi:[1,0]
	v_pk_mul_f32 v[44:45], v[44:45], v[96:97] op_sel_hi:[1,0]
	s_nop 0
	s_waitcnt lgkmcnt(5)
	v_mfma_f32_16x16x32_bf16 v[48:51], v[240:243], v[224:227], v[48:51]
	ds_read_b128 v[240:243], v94 offset:37184
	s_nop 0
	v_pk_mul_f32 v[38:39], v[38:39], v[96:97] op_sel_hi:[1,0]
	v_pk_mul_f32 v[36:37], v[36:37], v[96:97] op_sel_hi:[1,0]
	s_nop 0
	s_waitcnt lgkmcnt(5)
	v_mfma_f32_16x16x32_bf16 v[44:47], v[244:247], v[224:227], v[44:47]
	ds_read_b128 v[244:247], v94 offset:39488
	s_nop 0
	v_pk_mul_f32 v[42:43], v[42:43], v[96:97] op_sel_hi:[1,0]
	v_pk_mul_f32 v[40:41], v[40:41], v[96:97] op_sel_hi:[1,0]
	s_nop 0
	s_waitcnt lgkmcnt(5)
	v_mfma_f32_16x16x32_bf16 v[36:39], v[248:251], v[224:227], v[36:39]
	ds_read_b128 v[248:251], v94 offset:41792
	s_nop 0
	v_pk_mul_f32 v[34:35], v[34:35], v[96:97] op_sel_hi:[1,0]
	v_pk_mul_f32 v[32:33], v[32:33], v[96:97] op_sel_hi:[1,0]
	s_nop 0
	s_waitcnt lgkmcnt(5)
	v_mfma_f32_16x16x32_bf16 v[40:43], v[228:231], v[224:227], v[40:43]
	ds_read_b128 v[228:231], v94 offset:44096
	s_nop 0
	s_nop 0
	s_waitcnt lgkmcnt(5)
	v_mfma_f32_16x16x32_bf16 v[32:35], v[232:235], v[224:227], v[32:35]
	ds_read_b128 v[224:227], v94 offset:46400
	ds_read_b128 v[232:235], v94 offset:48704
	ds_read_b128 v[96:99], v68 offset:53312
	s_nop 0
	s_nop 0
	s_waitcnt lgkmcnt(0)
	v_mfma_f32_16x16x32_bf16 v[60:63], v[236:239], v[96:99], v[24:27]
	s_nop 2
	s_nop 0
	s_nop 0
	v_mfma_f32_16x16x32_bf16 v[56:59], v[240:243], v[96:99], v[28:31]
	s_nop 0
	s_nop 0
	v_mfma_f32_16x16x32_bf16 v[52:55], v[244:247], v[96:99], v[52:55]
	s_nop 0
	s_nop 0
	v_mfma_f32_16x16x32_bf16 v[48:51], v[248:251], v[96:99], v[48:51]
	s_nop 0
	s_nop 0
	v_mfma_f32_16x16x32_bf16 v[44:47], v[228:231], v[96:99], v[44:47]
	s_nop 0
	s_nop 0
	v_mfma_f32_16x16x32_bf16 v[36:39], v[224:227], v[96:99], v[36:39]
	s_nop 0
	s_nop 0
	v_mfma_f32_16x16x32_bf16 v[40:43], v[232:235], v[96:99], v[40:43]
	ds_read_b128 v[24:27], v94 offset:51008
	s_waitcnt lgkmcnt(0)
	s_waitcnt lgkmcnt(0)
	s_barrier
	v_mfma_f32_16x16x32_bf16 v[32:35], v[24:27], v[96:99], v[32:35]
	s_cbranch_scc0 .LBB0_486
	s_waitcnt vmcnt(2)
	v_mov_b32_e32 v28, v16
	v_mov_b32_e32 v29, v17
	v_mov_b32_e32 v30, v18
	v_mov_b32_e32 v31, v19
	s_waitcnt vmcnt(1)
	v_mov_b32_e32 v24, v20
	v_mov_b32_e32 v25, v21
	v_mov_b32_e32 v26, v22
	v_mov_b32_e32 v27, v23
	s_branch .LBB0_479

; DI float bflo(unsigned u) { return __uint_as_float(u << 16); }
; DI float bfhi(unsigned u) { return __uint_as_float(u & 0xffff0000u); }
; template <int PROBE, int SONLY, int CPS>
; DI void ssd_chunk_loop(const Params& p, int layer, int b, int e, int c0, f32x4 (&h)[8], float& dtot, bool write_final) {
;     ...
;     {
;       const int nb_ = b * 2048 + ((cc + 1 < c0 + CPS) ? (cc + 1) : cc) * 64;
; #pragma unroll
;       for (int i = 0; i < 4; ++i) {
;         const int idx = tid + 256 * i, r = idx >> 4, c16 = idx & 15;
;         if (!SONLY) pc[i] = *(const u32x4*)(XBC + (size_t)(nb_ + r) * 1280 + 1024 + g * 128 + c16 * 8);
;         pb[i] = *(const u32x4*)(XBC + (size_t)(nb_ + r) * 1280 + 768 + g * 128 + c16 * 8);
;       }
; #pragma unroll
;       for (int i = 0; i < 2; ++i) {
;         const int idx = tid + 256 * i, r = idx >> 3, c8 = idx & 7;
;         px[i] = *(const u32x4*)(XBC + (size_t)(nb_ + r) * 1280 + e * 64 + c8 * 8);
;       }
;       pru = PROJ[(size_t)(nb_ + lane) * NPAD + C_DT + e];
;     }
;     uint2 dx[4], dz[4];
;     if (!SONLY)
; #pragma unroll
;     for (int qt = 0; qt < 4; ++qt) {
;       const size_t row = (size_t)(base + qt * 16 + l15);
;       const int pcol = w * 16 + quad * 4;
;       dx[qt] = *(const uint2*)(XBC + row * 1280 + e * 64 + pcol);
;       dz[qt] = *(const uint2*)(PROJ + row * NPAD + C_Z + e * 64 + pcol);
;     }
;     __syncthreads();
;     dtot += acs_s[63];
;     if (!(PROBE & 2)) {
; #pragma unroll
;     for (int i = 0; i < 2; ++i) {
;       const int idx = tid + 256 * i, r = idx >> 3, c8 = idx & 7;
;       const float dtv = dt_s[r];
;       float f[8]; unpack8v(xr[i], f);
; #pragma unroll
;       for (int j = 0; j < 8; ++j) Xt[(c8 * 8 + j) * 72 + r] = f2bf(f[j] * dtv);
;     }
;     {
;       const int q = tid & 63, ng = tid >> 6;
;       const float dte = __expf(acs_s[63] - acs_s[q]);
; #pragma unroll
;       for (int i = 0; i < 8; ++i) {
;         const uint2 v = *(const uint2*)(Bs + q * 136 + ng * 32 + i * 4);
;         Bt2[(ng * 32 + i * 4 + 0) * 72 + q] = f2bf(bflo(v.x) * dte);
;         Bt2[(ng * 32 + i * 4 + 1) * 72 + q] = f2bf(bfhi(v.x) * dte);
;         Bt2[(ng * 32 + i * 4 + 2) * 72 + q] = f2bf(bflo(v.y) * dte);
;         Bt2[(ng * 32 + i * 4 + 3) * 72 + q] = f2bf(bfhi(v.y) * dte);
;       }
;     }
.LBB0_515:
	s_or_b64 exec, exec, s[84:85]
	s_cmpk_lg_i32 s13, 0x800
	s_cselect_b32 s2, s13, 0x7c0
	s_add_i32 s2, s2, s87
	v_or_b32_e32 v114, s2, v133
	v_mov_b64_e32 v[112:113], s[4:5]
	v_add_u32_e32 v124, s13, v242
	v_mad_u64_u32 v[114:115], s[6:7], v114, s97, v[112:113]
	s_mov_b32 s9, s3
	v_subrev_u32_e32 v160, 64, v124
	v_add_u32_e32 v32, s2, v175
	v_add_u32_e32 v40, s2, v177
	v_add_u32_e32 v48, s2, v178
	v_add_u32_e32 v56, s2, v179
	v_add_u32_e32 v96, s2, v176
	v_add_u32_e32 v98, s2, v180
	v_lshl_add_u64 v[114:115], v[114:115], 0, s[8:9]
	v_mad_u64_u32 v[118:119], s[6:7], v160, s97, v[112:113]
	s_lshl_b32 s2, s22, 1
	v_add_co_u32_e32 v114, vcc, s16, v114
	v_lshl_add_u64 v[118:119], v[118:119], 0, s[2:3]
	v_lshlrev_b64 v[120:121], 1, v[134:135]
	v_addc_co_u32_e32 v115, vcc, 0, v115, vcc
	v_lshl_add_u64 v[118:119], v[118:119], 0, v[120:121]
	v_mad_i64_i32 v[36:37], s[6:7], v32, s34, v[146:147]
	v_mad_i64_i32 v[44:45], s[6:7], v40, s34, v[146:147]
	v_mad_i64_i32 v[52:53], s[6:7], v48, s34, v[146:147]
	v_mad_i64_i32 v[60:61], s[6:7], v56, s34, v[146:147]
	v_mad_i64_i32 v[96:97], s[6:7], v96, s34, v[130:131]
	v_mad_i64_i32 v[100:101], s[6:7], v98, s34, v[130:131]
	v_add_co_u32_e32 v118, vcc, s10, v118
	v_subrev_u32_e32 v164, 48, v124
	global_load_dwordx4 v[32:35], v[36:37], off offset:2048
	s_nop 0
	global_load_dwordx4 v[36:39], v[36:37], off offset:1536
	s_nop 0
	global_load_dwordx4 v[40:43], v[44:45], off offset:2048
	s_nop 0
	global_load_dwordx4 v[44:47], v[44:45], off offset:1536
	s_nop 0
	global_load_dwordx4 v[48:51], v[52:53], off offset:2048
	s_nop 0
	global_load_dwordx4 v[52:55], v[52:53], off offset:1536
	s_nop 0
	global_load_dwordx4 v[56:59], v[60:61], off offset:2048
	s_nop 0
	global_load_dwordx4 v[60:63], v[60:61], off offset:1536
	s_nop 0
	global_load_dwordx4 v[96:99], v[96:97], off
	s_nop 0
	global_load_dwordx4 v[100:103], v[100:101], off
	v_mad_u64_u32 v[116:117], s[6:7], v160, s34, v[136:137]
	v_addc_co_u32_e32 v119, vcc, 0, v119, vcc
	v_mad_u64_u32 v[122:123], s[6:7], v164, s34, v[136:137]
	global_load_ushort v163, v[114:115], off offset:1536
	global_load_dwordx2 v[172:173], v[116:117], off
	global_load_dwordx2 v[170:171], v[118:119], off offset:1536
	global_load_dwordx2 v[166:167], v[122:123], off
	v_mad_u64_u32 v[114:115], s[6:7], v164, s97, v[112:113]
	v_lshl_add_u64 v[114:115], v[114:115], 0, s[2:3]
	v_subrev_u32_e32 v154, 32, v124
	v_lshl_add_u64 v[114:115], v[114:115], 0, v[120:121]
	v_mad_u64_u32 v[118:119], s[6:7], v154, s97, v[112:113]
	v_add_co_u32_e32 v114, vcc, s10, v114
	v_lshl_add_u64 v[118:119], v[118:119], 0, s[2:3]
	v_add_u32_e32 v148, -16, v124
	v_addc_co_u32_e32 v115, vcc, 0, v115, vcc
	v_lshl_add_u64 v[118:119], v[118:119], 0, v[120:121]
	v_mad_u64_u32 v[112:113], s[6:7], v148, s97, v[112:113]
	v_add_co_u32_e32 v118, vcc, s10, v118
	v_lshl_add_u64 v[112:113], v[112:113], 0, s[2:3]
	s_nop 0
	v_addc_co_u32_e32 v119, vcc, 0, v119, vcc
	v_lshl_add_u64 v[112:113], v[112:113], 0, v[120:121]
	v_add_co_u32_e32 v112, vcc, s10, v112
	v_mad_u64_u32 v[116:117], s[6:7], v154, s34, v[136:137]
	s_nop 0
	v_addc_co_u32_e32 v113, vcc, 0, v113, vcc
	v_mad_u64_u32 v[122:123], s[6:7], v148, s34, v[136:137]
	global_load_dwordx2 v[168:169], v[114:115], off offset:1536
	global_load_dwordx2 v[158:159], v[116:117], off
	global_load_dwordx2 v[156:157], v[118:119], off offset:1536
	global_load_dwordx2 v[150:151], v[122:123], off
	global_load_dwordx2 v[152:153], v[112:113], off offset:1536
	s_waitcnt lgkmcnt(0)
	s_barrier
	ds_read_b32 v113, v219
	s_waitcnt vmcnt(21)
	v_lshlrev_b32_e32 v114, 16, v108
	v_and_b32_e32 v108, 0xffff0000, v108
	v_mov_b32_e32 v112, s20
	v_lshlrev_b32_e32 v115, 16, v109
	s_nop 0
	s_waitcnt lgkmcnt(0)
	v_mul_f32_e32 v108, v113, v108
	v_cvt_pk_bf16_f32 v108, v108, s0
	ds_read_b32 v112, v112
	ds_read_b32 v118, v220
	ds_read_b32 v119, v205
	ds_write_b16 v243, v108 offset:53392
	v_mul_f32_e32 v108, v113, v115
	v_and_b32_e32 v109, 0xffff0000, v109
	v_cvt_pk_bf16_f32 v108, v108, s0
	ds_write_b16 v243, v108 offset:53536
	v_mul_f32_e32 v108, v113, v109
	v_lshlrev_b32_e32 v116, 16, v110
	v_cvt_pk_bf16_f32 v108, v108, s0
	ds_write_b16 v243, v108 offset:53680
	v_mul_f32_e32 v108, v113, v116
	v_and_b32_e32 v110, 0xffff0000, v110
	v_cvt_pk_bf16_f32 v108, v108, s0
	ds_write_b16 v243, v108 offset:53824
	v_mul_f32_e32 v108, v113, v110
	v_lshlrev_b32_e32 v117, 16, v111
	v_cvt_pk_bf16_f32 v108, v108, s0
	ds_write_b16 v243, v108 offset:53968
	v_mul_f32_e32 v108, v113, v117
	v_and_b32_e32 v111, 0xffff0000, v111
	v_cvt_pk_bf16_f32 v108, v108, s0
	ds_write_b16 v243, v108 offset:54112
	v_mul_f32_e32 v108, v113, v111
	v_cvt_pk_bf16_f32 v108, v108, s0
	ds_write_b16 v243, v108 offset:54256
	s_waitcnt vmcnt(20)
	v_lshlrev_b32_e32 v108, 16, v104
	v_and_b32_e32 v104, 0xffff0000, v104
	v_mul_f32_e32 v114, v113, v114
	s_nop 0
	s_waitcnt lgkmcnt(8)
	v_mul_f32_e32 v104, v118, v104
	v_cvt_pk_bf16_f32 v114, v114, s0
	v_lshlrev_b32_e32 v109, 16, v105
	v_cvt_pk_bf16_f32 v104, v104, s0
	ds_write_b16 v243, v114 offset:53248
	ds_write_b16 v244, v104 offset:53392
	v_mul_f32_e32 v104, v118, v109
	v_and_b32_e32 v105, 0xffff0000, v105
	v_cvt_pk_bf16_f32 v104, v104, s0
	ds_write_b16 v244, v104 offset:53536
	v_mul_f32_e32 v104, v118, v105
	v_lshlrev_b32_e32 v110, 16, v106
	v_cvt_pk_bf16_f32 v104, v104, s0
	ds_write_b16 v244, v104 offset:53680
	v_mul_f32_e32 v104, v118, v110
	v_and_b32_e32 v106, 0xffff0000, v106
	v_cvt_pk_bf16_f32 v104, v104, s0
	ds_write_b16 v244, v104 offset:53824
	v_mul_f32_e32 v104, v118, v106
	v_lshlrev_b32_e32 v111, 16, v107
	v_cvt_pk_bf16_f32 v104, v104, s0
	ds_write_b16 v244, v104 offset:53968
	v_mul_f32_e32 v104, v118, v111
	v_and_b32_e32 v107, 0xffff0000, v107
	v_cvt_pk_bf16_f32 v104, v104, s0
	v_mul_f32_e32 v108, v118, v108
	ds_write_b16 v244, v104 offset:54112
	v_mul_f32_e32 v104, v118, v107
	v_cvt_pk_bf16_f32 v108, v108, s0
	v_cvt_pk_bf16_f32 v104, v104, s0
	ds_write_b16 v244, v108 offset:53248
	ds_write_b16 v244, v104 offset:54256
	v_add_u32_e32 v107, v206, v207
	ds_read_b64 v[0:1], v107 offset:17408
	ds_read_b64 v[4:5], v107 offset:17416
	ds_read_b64 v[8:9], v107 offset:17424
	ds_read_b64 v[12:13], v107 offset:17432
	ds_read_b64 v[16:17], v107 offset:17440
	ds_read_b64 v[20:21], v107 offset:17448
	ds_read_b64 v[24:25], v107 offset:17456
	s_nop 0
	s_waitcnt lgkmcnt(15)
; DI float bflo(unsigned u) { return __uint_as_float(u << 16); }
; DI float bfhi(unsigned u) { return __uint_as_float(u & 0xffff0000u); }
; DI f32x4 mfma16(bf16x8 a, bf16x8 b, f32x4 c) { return __builtin_amdgcn_mfma_f32_16x16x32_bf16(a, b, c, 0, 0, 0); }
; template <int PROBE, int SONLY, int CPS>
; DI void ssd_chunk_loop(const Params& p, int layer, int b, int e, int c0, f32x4 (&h)[8], float& dtot, bool write_final) {
;     ...
;     {
;       const int q = tid & 63, ng = tid >> 6;
;       const float dte = __expf(acs_s[63] - acs_s[q]);
; #pragma unroll
;       for (int i = 0; i < 8; ++i) {
;         const uint2 v = *(const uint2*)(Bs + q * 136 + ng * 32 + i * 4);
;         Bt2[(ng * 32 + i * 4 + 0) * 72 + q] = f2bf(bflo(v.x) * dte);
;         Bt2[(ng * 32 + i * 4 + 1) * 72 + q] = f2bf(bfhi(v.x) * dte);
;         Bt2[(ng * 32 + i * 4 + 2) * 72 + q] = f2bf(bflo(v.y) * dte);
;         Bt2[(ng * 32 + i * 4 + 3) * 72 + q] = f2bf(bfhi(v.y) * dte);
;       }
;     }
;     ...
;     if (!(PROBE & 4) && !SONLY) {
;       const int q = w * 16 + l15;
;       const float aq = acs_s[q];
;       bf16x8 cfr[4];
; #pragma unroll
;       for (int ks = 0; ks < 4; ++ks) cfr[ks] = ldfrag(Cs, 136, w * 16, ks * 32, lane);
; #pragma unroll
;       for (int st = 0; st < 4; ++st) {
;         uint2 ov;
;         const int s0 = st * 16 + quad * 4;
;         {
;           f32x4 acc = (f32x4){0.f, 0.f, 0.f, 0.f};
; #pragma unroll
;           for (int ks = 0; ks < 4; ++ks) acc = mfma16(ldfrag(Bs, 136, st * 16, ks * 32, lane), cfr[ks], acc);
;           float v[4];
; #pragma unroll
;           for (int r = 0; r < 4; ++r) { const int s = s0 + r; v[r] = (s <= q) ? acc[r] * __expf(fminf(aq - acs_s[s], 0.f)) : 0.f; }
	v_sub_f32_e32 v106, v112, v119
	s_nop 0
	v_mul_f32_e32 v106, 0x3fb8aa3b, v106
	v_exp_f32_e32 v106, v106
	v_add_u32_e32 v125, v210, v223
	v_mov_b32_e32 v127, 0
	s_nop 0
	s_waitcnt lgkmcnt(6)
	v_lshlrev_b32_e32 v108, 16, v0
	v_and_b32_e32 v104, 0xffff0000, v0
	v_mul_f32_e32 v108, v106, v108
	v_mul_f32_e32 v104, v106, v104
	v_cvt_pk_bf16_f32 v108, v108, s0
	v_cvt_pk_bf16_f32 v104, v104, s0
	ds_write_b16 v221, v108 offset:34816
	ds_write_b16 v222, v104 offset:34960
	v_lshlrev_b32_e32 v104, 16, v1
	v_mul_f32_e32 v104, v106, v104
	v_cvt_pk_bf16_f32 v104, v104, s0
	ds_write_b16 v222, v104 offset:35104
	v_and_b32_e32 v104, 0xffff0000, v1
	v_mul_f32_e32 v104, v106, v104
	v_cvt_pk_bf16_f32 v104, v104, s0
	ds_write_b16 v222, v104 offset:35248
	s_nop 0
	v_mov_b32_e32 v149, 0
	s_nop 0
	s_waitcnt lgkmcnt(9)
	v_lshlrev_b32_e32 v108, 16, v4
	v_and_b32_e32 v104, 0xffff0000, v4
	v_mul_f32_e32 v108, v106, v108
	v_mul_f32_e32 v104, v106, v104
	v_cvt_pk_bf16_f32 v108, v108, s0
	v_cvt_pk_bf16_f32 v104, v104, s0
	ds_write_b16 v221, v108 offset:35392
	ds_write_b16 v222, v104 offset:35536
	v_lshlrev_b32_e32 v104, 16, v5
	v_mul_f32_e32 v104, v106, v104
	v_cvt_pk_bf16_f32 v104, v104, s0
	ds_write_b16 v222, v104 offset:35680
	v_and_b32_e32 v104, 0xffff0000, v5
	v_mul_f32_e32 v104, v106, v104
	v_cvt_pk_bf16_f32 v104, v104, s0
	ds_write_b16 v222, v104 offset:35824
	s_nop 0
	s_nop 0
	s_waitcnt lgkmcnt(12)
	v_lshlrev_b32_e32 v108, 16, v8
	v_and_b32_e32 v104, 0xffff0000, v8
	v_mul_f32_e32 v108, v106, v108
	v_mul_f32_e32 v104, v106, v104
	v_cvt_pk_bf16_f32 v108, v108, s0
	v_cvt_pk_bf16_f32 v104, v104, s0
	ds_write_b16 v221, v108 offset:35968
	ds_write_b16 v222, v104 offset:36112
	v_lshlrev_b32_e32 v104, 16, v9
	v_mul_f32_e32 v104, v106, v104
	v_cvt_pk_bf16_f32 v104, v104, s0
	ds_write_b16 v222, v104 offset:36256
	v_and_b32_e32 v104, 0xffff0000, v9
	v_mul_f32_e32 v104, v106, v104
	v_cvt_pk_bf16_f32 v104, v104, s0
	ds_write_b16 v222, v104 offset:36400
	s_nop 0
	s_nop 0
	s_waitcnt lgkmcnt(15)
	v_lshlrev_b32_e32 v108, 16, v12
	v_and_b32_e32 v104, 0xffff0000, v12
	v_mul_f32_e32 v108, v106, v108
	v_mul_f32_e32 v104, v106, v104
	v_cvt_pk_bf16_f32 v108, v108, s0
	v_cvt_pk_bf16_f32 v104, v104, s0
	ds_write_b16 v221, v108 offset:36544
	ds_write_b16 v222, v104 offset:36688
	v_lshlrev_b32_e32 v104, 16, v13
	v_mul_f32_e32 v104, v106, v104
	v_cvt_pk_bf16_f32 v104, v104, s0
	ds_write_b16 v222, v104 offset:36832
	v_and_b32_e32 v104, 0xffff0000, v13
	v_mul_f32_e32 v104, v106, v104
	v_cvt_pk_bf16_f32 v104, v104, s0
	ds_write_b16 v222, v104 offset:36976
	s_nop 0
	s_nop 0
	s_waitcnt lgkmcnt(15)
	v_lshlrev_b32_e32 v108, 16, v16
	v_and_b32_e32 v104, 0xffff0000, v16
	v_mul_f32_e32 v108, v106, v108
	v_mul_f32_e32 v104, v106, v104
	v_cvt_pk_bf16_f32 v108, v108, s0
	v_cvt_pk_bf16_f32 v104, v104, s0
	ds_write_b16 v221, v108 offset:37120
	ds_write_b16 v222, v104 offset:37264
	v_lshlrev_b32_e32 v104, 16, v17
	v_mul_f32_e32 v104, v106, v104
	v_cvt_pk_bf16_f32 v104, v104, s0
	ds_write_b16 v222, v104 offset:37408
	v_and_b32_e32 v104, 0xffff0000, v17
	v_mul_f32_e32 v104, v106, v104
	v_cvt_pk_bf16_f32 v104, v104, s0
	ds_write_b16 v222, v104 offset:37552
	s_nop 0
	s_nop 0
	s_waitcnt lgkmcnt(15)
	v_lshlrev_b32_e32 v108, 16, v20
	v_and_b32_e32 v104, 0xffff0000, v20
	v_mul_f32_e32 v108, v106, v108
	v_mul_f32_e32 v104, v106, v104
	v_cvt_pk_bf16_f32 v108, v108, s0
	v_cvt_pk_bf16_f32 v104, v104, s0
	ds_write_b16 v221, v108 offset:37696
	ds_write_b16 v222, v104 offset:37840
	v_lshlrev_b32_e32 v104, 16, v21
	v_mul_f32_e32 v104, v106, v104
	v_cvt_pk_bf16_f32 v104, v104, s0
	ds_write_b16 v222, v104 offset:37984
	v_and_b32_e32 v104, 0xffff0000, v21
	v_mul_f32_e32 v104, v106, v104
	v_cvt_pk_bf16_f32 v104, v104, s0
	ds_write_b16 v222, v104 offset:38128
	s_nop 0
	s_nop 0
	s_waitcnt lgkmcnt(15)
	v_lshlrev_b32_e32 v108, 16, v24
	v_and_b32_e32 v104, 0xffff0000, v24
	v_mul_f32_e32 v108, v106, v108
	v_mul_f32_e32 v104, v106, v104
	v_cvt_pk_bf16_f32 v108, v108, s0
	v_cvt_pk_bf16_f32 v104, v104, s0
	ds_write_b16 v221, v108 offset:38272
	ds_write_b16 v222, v104 offset:38416
	v_lshlrev_b32_e32 v104, 16, v25
	v_mul_f32_e32 v104, v106, v104
	v_cvt_pk_bf16_f32 v104, v104, s0
	ds_write_b16 v222, v104 offset:38560
	v_and_b32_e32 v104, 0xffff0000, v25
	v_mul_f32_e32 v104, v106, v104
	v_cvt_pk_bf16_f32 v104, v104, s0
	ds_write_b16 v222, v104 offset:38704
	ds_read_b64 v[104:105], v107 offset:17464
	s_nop 0
	s_waitcnt lgkmcnt(0)
	v_lshlrev_b32_e32 v107, 16, v104
	v_and_b32_e32 v104, 0xffff0000, v104
	v_mul_f32_e32 v107, v106, v107
	v_mul_f32_e32 v104, v106, v104
	v_cvt_pk_bf16_f32 v107, v107, s0
	v_cvt_pk_bf16_f32 v104, v104, s0
	ds_write_b16 v221, v107 offset:38848
	ds_write_b16 v222, v104 offset:38992
	v_lshlrev_b32_e32 v104, 16, v105
	v_mul_f32_e32 v104, v106, v104
	v_cvt_pk_bf16_f32 v104, v104, s0
	ds_write_b16 v222, v104 offset:39136
	v_and_b32_e32 v104, 0xffff0000, v105
	v_mul_f32_e32 v104, v106, v104
	v_cvt_pk_bf16_f32 v104, v104, s0
	ds_write_b16 v222, v104 offset:39280
	s_waitcnt lgkmcnt(0)
	s_waitcnt lgkmcnt(0)
	s_barrier
	ds_read_b32 v0, v225
	ds_read_b32 v1, v226
	ds_read_b32 v2, v228
	ds_read_b32 v3, v229
	ds_read_b32 v4, v230
	ds_read_b32 v5, v231
	ds_read_b32 v6, v232
	ds_read_b32 v7, v233
	ds_read_b32 v8, v234
	ds_read_b32 v9, v235
	ds_read_b32 v10, v236
	ds_read_b32 v11, v239
	s_waitcnt lgkmcnt(8)
	ds_read_b32 v12, v224
	ds_read_b32 v13, v224 offset:4
	ds_read_b32 v14, v237
	ds_read_b32 v15, v238
	s_waitcnt lgkmcnt(4)
	ds_read_b128 v[104:107], v125 offset:17408
	ds_read_b128 v[108:111], v209
	ds_read_b128 v[116:119], v125 offset:17472
	s_waitcnt lgkmcnt(1)
	v_mfma_f32_16x16x32_bf16 v[120:123], v[104:107], v[108:111], 0
	ds_read_b128 v[248:251], v125 offset:17536
	ds_read_b128 v[112:115], v209 offset:64
	ds_read_b128 v[104:107], v209 offset:128
	s_waitcnt lgkmcnt(1)
	v_mfma_f32_16x16x32_bf16 v[116:119], v[116:119], v[112:115], v[120:123]
	s_nop 2
	ds_read_b128 v[120:123], v125 offset:17600
	s_waitcnt lgkmcnt(1)
	v_mfma_f32_16x16x32_bf16 v[248:251], v[248:251], v[104:107], v[116:119]
	s_nop 2
	ds_read_b128 v[116:119], v209 offset:192
	ds_read_b32 v124, v208
	s_waitcnt lgkmcnt(1)
	v_mfma_f32_16x16x32_bf16 v[120:123], v[120:123], v[116:119], v[248:251]
	s_and_saveexec_b64 s[6:7], s[52:53]
	s_cbranch_execnz .LBB0_553
	s_or_b64 exec, exec, s[6:7]
	s_nop 4
	v_mov_b32_e32 v120, 0
	s_and_saveexec_b64 s[6:7], s[54:55]
	s_cbranch_execnz .LBB0_554

; DI float bflo(unsigned u) { return __uint_as_float(u << 16); }
; DI float bfhi(unsigned u) { return __uint_as_float(u & 0xffff0000u); }
; template <int PROBE, int SONLY, int CPS>
; DI void ssd_chunk_loop(const Params& p, int layer, int b, int e, int c0, f32x4 (&h)[8], float& dtot, bool write_final) {
;     ...
;     {
;       const int nb_ = b * 2048 + ((cc + 1 < c0 + CPS) ? (cc + 1) : cc) * 64;
; #pragma unroll
;       for (int i = 0; i < 4; ++i) {
;         const int idx = tid + 256 * i, r = idx >> 4, c16 = idx & 15;
;         if (!SONLY) pc[i] = *(const u32x4*)(XBC + (size_t)(nb_ + r) * 1280 + 1024 + g * 128 + c16 * 8);
;         pb[i] = *(const u32x4*)(XBC + (size_t)(nb_ + r) * 1280 + 768 + g * 128 + c16 * 8);
;       }
; #pragma unroll
;       for (int i = 0; i < 2; ++i) {
;         const int idx = tid + 256 * i, r = idx >> 3, c8 = idx & 7;
;         px[i] = *(const u32x4*)(XBC + (size_t)(nb_ + r) * 1280 + e * 64 + c8 * 8);
;       }
;       pru = PROJ[(size_t)(nb_ + lane) * NPAD + C_DT + e];
;     }
;     uint2 dx[4], dz[4];
;     if (!SONLY)
; #pragma unroll
;     for (int qt = 0; qt < 4; ++qt) {
;       const size_t row = (size_t)(base + qt * 16 + l15);
;       const int pcol = w * 16 + quad * 4;
;       dx[qt] = *(const uint2*)(XBC + row * 1280 + e * 64 + pcol);
;       dz[qt] = *(const uint2*)(PROJ + row * NPAD + C_Z + e * 64 + pcol);
;     }
;     __syncthreads();
;     dtot += acs_s[63];
;     if (!(PROBE & 2)) {
; #pragma unroll
;     for (int i = 0; i < 2; ++i) {
;       const int idx = tid + 256 * i, r = idx >> 3, c8 = idx & 7;
;       const float dtv = dt_s[r];
;       float f[8]; unpack8v(xr[i], f);
; #pragma unroll
;       for (int j = 0; j < 8; ++j) Xt[(c8 * 8 + j) * 72 + r] = f2bf(f[j] * dtv);
;     }
;     {
;       const int q = tid & 63, ng = tid >> 6;
;       const float dte = __expf(acs_s[63] - acs_s[q]);
; #pragma unroll
;       for (int i = 0; i < 8; ++i) {
;         const uint2 v = *(const uint2*)(Bs + q * 136 + ng * 32 + i * 4);
;         Bt2[(ng * 32 + i * 4 + 0) * 72 + q] = f2bf(bflo(v.x) * dte);
;         Bt2[(ng * 32 + i * 4 + 1) * 72 + q] = f2bf(bfhi(v.x) * dte);
;         Bt2[(ng * 32 + i * 4 + 2) * 72 + q] = f2bf(bflo(v.y) * dte);
;         Bt2[(ng * 32 + i * 4 + 3) * 72 + q] = f2bf(bfhi(v.y) * dte);
;       }
;     }
.LBB0_567:
	s_or_b64 exec, exec, s[8:9]
	s_add_i32 s8, s19, 1
	s_cmp_lt_i32 s8, s18
	s_cselect_b32 s6, s8, s19
	s_lshl_b32 s6, s6, 6
	s_add_i32 s9, s6, s2
	v_or_b32_e32 v82, s9, v142
	v_mov_b64_e32 v[80:81], s[4:5]
	v_mad_i64_i32 v[82:83], s[6:7], v82, s97, v[80:81]
	v_add_u32_e32 v136, s15, v210
	v_lshl_add_u64 v[82:83], v[100:101], 1, v[82:83]
	v_mad_i64_i32 v[86:87], s[6:7], v136, s97, v[80:81]
	v_add_co_u32_e32 v82, vcc, s16, v82
	v_lshl_add_u64 v[86:87], v[86:87], 0, s[86:87]
	v_lshlrev_b64 v[88:89], 1, v[102:103]
	v_add_u32_e32 v32, s9, v143
	v_add_u32_e32 v40, s9, v145
	v_add_u32_e32 v48, s9, v146
	v_add_u32_e32 v56, s9, v147
	v_add_u32_e32 v64, s9, v144
	v_add_u32_e32 v66, s9, v148
	v_addc_co_u32_e32 v83, vcc, 0, v83, vcc
	v_lshl_add_u64 v[86:87], v[86:87], 0, v[88:89]
	v_mad_i64_i32 v[36:37], s[6:7], v32, s34, v[116:117]
	v_mad_i64_i32 v[44:45], s[6:7], v40, s34, v[116:117]
	v_mad_i64_i32 v[52:53], s[6:7], v48, s34, v[116:117]
	v_mad_i64_i32 v[60:61], s[6:7], v56, s34, v[116:117]
	v_mad_i64_i32 v[64:65], s[6:7], v64, s34, v[98:99]
	v_mad_i64_i32 v[68:69], s[6:7], v66, s34, v[98:99]
	v_add_co_u32_e32 v86, vcc, s10, v86
	v_add_u32_e32 v130, 16, v136
	global_load_dwordx4 v[32:35], v[36:37], off offset:2048
	s_nop 0
	global_load_dwordx4 v[36:39], v[36:37], off offset:1536
	s_nop 0
	global_load_dwordx4 v[40:43], v[44:45], off offset:2048
	s_nop 0
	global_load_dwordx4 v[44:47], v[44:45], off offset:1536
	s_nop 0
	global_load_dwordx4 v[48:51], v[52:53], off offset:2048
	s_nop 0
	global_load_dwordx4 v[52:55], v[52:53], off offset:1536
	s_nop 0
	global_load_dwordx4 v[56:59], v[60:61], off offset:2048
	s_nop 0
	global_load_dwordx4 v[60:63], v[60:61], off offset:1536
	s_nop 0
	global_load_dwordx4 v[64:67], v[64:65], off
	s_nop 0
	global_load_dwordx4 v[68:71], v[68:69], off
	v_mad_i64_i32 v[84:85], s[6:7], v136, s34, v[104:105]
	v_addc_co_u32_e32 v87, vcc, 0, v87, vcc
	v_mad_i64_i32 v[90:91], s[6:7], v130, s34, v[104:105]
	global_load_ushort v163, v[82:83], off offset:1536
	global_load_dwordx2 v[140:141], v[84:85], off
	global_load_dwordx2 v[138:139], v[86:87], off offset:1536
	global_load_dwordx2 v[132:133], v[90:91], off
	v_mad_i64_i32 v[82:83], s[6:7], v130, s97, v[80:81]
	v_lshl_add_u64 v[82:83], v[82:83], 0, s[86:87]
	v_add_u32_e32 v124, 32, v136
	v_lshl_add_u64 v[82:83], v[82:83], 0, v[88:89]
	v_mad_i64_i32 v[86:87], s[6:7], v124, s97, v[80:81]
	v_add_co_u32_e32 v82, vcc, s10, v82
	v_lshl_add_u64 v[86:87], v[86:87], 0, s[86:87]
	v_add_u32_e32 v118, 48, v136
	v_addc_co_u32_e32 v83, vcc, 0, v83, vcc
	v_lshl_add_u64 v[86:87], v[86:87], 0, v[88:89]
	v_mad_i64_i32 v[80:81], s[6:7], v118, s97, v[80:81]
	v_add_co_u32_e32 v86, vcc, s10, v86
	v_lshl_add_u64 v[80:81], v[80:81], 0, s[86:87]
	s_nop 0
	v_addc_co_u32_e32 v87, vcc, 0, v87, vcc
	v_lshl_add_u64 v[80:81], v[80:81], 0, v[88:89]
	v_add_co_u32_e32 v80, vcc, s10, v80
	v_mad_i64_i32 v[84:85], s[6:7], v124, s34, v[104:105]
	s_nop 0
	v_addc_co_u32_e32 v81, vcc, 0, v81, vcc
	v_mad_i64_i32 v[90:91], s[6:7], v118, s34, v[104:105]
	global_load_dwordx2 v[134:135], v[82:83], off offset:1536
	global_load_dwordx2 v[128:129], v[84:85], off
	global_load_dwordx2 v[126:127], v[86:87], off offset:1536
	global_load_dwordx2 v[120:121], v[90:91], off
	global_load_dwordx2 v[122:123], v[80:81], off offset:1536
	s_waitcnt lgkmcnt(0)
	s_barrier
	ds_read_b32 v81, v169
	s_waitcnt vmcnt(21)
	v_lshlrev_b32_e32 v82, 16, v76
	v_and_b32_e32 v76, 0xffff0000, v76
	v_mov_b32_e32 v80, s20
	v_lshlrev_b32_e32 v83, 16, v77
	s_nop 0
	s_waitcnt lgkmcnt(0)
	v_mul_f32_e32 v76, v81, v76
	v_cvt_pk_bf16_f32 v76, v76, s0
	ds_read_b32 v80, v80
	ds_read_b32 v86, v170
	ds_read_b32 v87, v151
	ds_write_b16 v213, v76 offset:53392
	v_mul_f32_e32 v76, v81, v83
	v_and_b32_e32 v77, 0xffff0000, v77
	v_cvt_pk_bf16_f32 v76, v76, s0
	ds_write_b16 v213, v76 offset:53536
	v_mul_f32_e32 v76, v81, v77
	v_lshlrev_b32_e32 v84, 16, v78
	v_cvt_pk_bf16_f32 v76, v76, s0
	ds_write_b16 v213, v76 offset:53680
	v_mul_f32_e32 v76, v81, v84
	v_and_b32_e32 v78, 0xffff0000, v78
	v_cvt_pk_bf16_f32 v76, v76, s0
	ds_write_b16 v213, v76 offset:53824
	v_mul_f32_e32 v76, v81, v78
	v_lshlrev_b32_e32 v85, 16, v79
	v_cvt_pk_bf16_f32 v76, v76, s0
	ds_write_b16 v213, v76 offset:53968
	v_mul_f32_e32 v76, v81, v85
	v_and_b32_e32 v79, 0xffff0000, v79
	v_cvt_pk_bf16_f32 v76, v76, s0
	ds_write_b16 v213, v76 offset:54112
	v_mul_f32_e32 v76, v81, v79
	v_cvt_pk_bf16_f32 v76, v76, s0
	ds_write_b16 v213, v76 offset:54256
	s_waitcnt vmcnt(20)
	v_lshlrev_b32_e32 v76, 16, v72
	v_and_b32_e32 v72, 0xffff0000, v72
	v_mul_f32_e32 v82, v81, v82
	s_nop 0
	s_waitcnt lgkmcnt(8)
	v_mul_f32_e32 v72, v86, v72
	v_cvt_pk_bf16_f32 v82, v82, s0
	v_lshlrev_b32_e32 v77, 16, v73
	v_cvt_pk_bf16_f32 v72, v72, s0
	ds_write_b16 v213, v82 offset:53248
	ds_write_b16 v214, v72 offset:53392
	v_mul_f32_e32 v72, v86, v77
	v_and_b32_e32 v73, 0xffff0000, v73
	v_cvt_pk_bf16_f32 v72, v72, s0
	ds_write_b16 v214, v72 offset:53536
	v_mul_f32_e32 v72, v86, v73
	v_lshlrev_b32_e32 v78, 16, v74
	v_cvt_pk_bf16_f32 v72, v72, s0
	ds_write_b16 v214, v72 offset:53680
	v_mul_f32_e32 v72, v86, v78
	v_and_b32_e32 v74, 0xffff0000, v74
	v_cvt_pk_bf16_f32 v72, v72, s0
	ds_write_b16 v214, v72 offset:53824
	v_mul_f32_e32 v72, v86, v74
	v_lshlrev_b32_e32 v79, 16, v75
	v_cvt_pk_bf16_f32 v72, v72, s0
	ds_write_b16 v214, v72 offset:53968
	v_mul_f32_e32 v72, v86, v79
	v_and_b32_e32 v75, 0xffff0000, v75
	v_cvt_pk_bf16_f32 v72, v72, s0
	v_mul_f32_e32 v76, v86, v76
	ds_write_b16 v214, v72 offset:54112
	v_mul_f32_e32 v72, v86, v75
	v_cvt_pk_bf16_f32 v76, v76, s0
	v_cvt_pk_bf16_f32 v72, v72, s0
	ds_write_b16 v214, v76 offset:53248
	ds_write_b16 v214, v72 offset:54256
	v_add_u32_e32 v75, v152, v153
	ds_read_b64 v[224:225], v75 offset:17408
	ds_read_b64 v[228:229], v75 offset:17416
	ds_read_b64 v[232:233], v75 offset:17424
	ds_read_b64 v[236:237], v75 offset:17432
	ds_read_b64 v[240:241], v75 offset:17440
	ds_read_b64 v[244:245], v75 offset:17448
	ds_read_b64 v[248:249], v75 offset:17456
	s_nop 0
	s_waitcnt lgkmcnt(15)
; DI float bflo(unsigned u) { return __uint_as_float(u << 16); }
; DI float bfhi(unsigned u) { return __uint_as_float(u & 0xffff0000u); }
; DI f32x4 mfma16(bf16x8 a, bf16x8 b, f32x4 c) { return __builtin_amdgcn_mfma_f32_16x16x32_bf16(a, b, c, 0, 0, 0); }
; template <int PROBE, int SONLY, int CPS>
; DI void ssd_chunk_loop(const Params& p, int layer, int b, int e, int c0, f32x4 (&h)[8], float& dtot, bool write_final) {
;     ...
;     {
;       const int q = tid & 63, ng = tid >> 6;
;       const float dte = __expf(acs_s[63] - acs_s[q]);
; #pragma unroll
;       for (int i = 0; i < 8; ++i) {
;         const uint2 v = *(const uint2*)(Bs + q * 136 + ng * 32 + i * 4);
;         Bt2[(ng * 32 + i * 4 + 0) * 72 + q] = f2bf(bflo(v.x) * dte);
;         Bt2[(ng * 32 + i * 4 + 1) * 72 + q] = f2bf(bfhi(v.x) * dte);
;         Bt2[(ng * 32 + i * 4 + 2) * 72 + q] = f2bf(bflo(v.y) * dte);
;         Bt2[(ng * 32 + i * 4 + 3) * 72 + q] = f2bf(bfhi(v.y) * dte);
;       }
;     }
;     }
;     __syncthreads();
;     if (!(PROBE & 4) && !SONLY) {
;       const int q = w * 16 + l15;
;       const float aq = acs_s[q];
;       bf16x8 cfr[4];
; #pragma unroll
;       for (int ks = 0; ks < 4; ++ks) cfr[ks] = ldfrag(Cs, 136, w * 16, ks * 32, lane);
; #pragma unroll
;       for (int st = 0; st < 4; ++st) {
;         uint2 ov;
;         const int s0 = st * 16 + quad * 4;
;         {
;           f32x4 acc = (f32x4){0.f, 0.f, 0.f, 0.f};
; #pragma unroll
;           for (int ks = 0; ks < 4; ++ks) acc = mfma16(ldfrag(Bs, 136, st * 16, ks * 32, lane), cfr[ks], acc);
;           float v[4];
; #pragma unroll
;           for (int r = 0; r < 4; ++r) { const int s = s0 + r; v[r] = (s <= q) ? acc[r] * __expf(fminf(aq - acs_s[s], 0.f)) : 0.f; }
	v_sub_f32_e32 v74, v80, v87
	s_nop 0
	v_mul_f32_e32 v74, 0x3fb8aa3b, v74
	v_exp_f32_e32 v74, v74
	v_add_u32_e32 v93, v156, v173
	v_mov_b32_e32 v95, 0
	s_nop 0
	s_waitcnt lgkmcnt(6)
	v_lshlrev_b32_e32 v76, 16, v224
	v_and_b32_e32 v72, 0xffff0000, v224
	v_mul_f32_e32 v76, v74, v76
	v_mul_f32_e32 v72, v74, v72
	v_cvt_pk_bf16_f32 v76, v76, s0
	v_cvt_pk_bf16_f32 v72, v72, s0
	ds_write_b16 v171, v76 offset:34816
	ds_write_b16 v172, v72 offset:34960
	v_lshlrev_b32_e32 v72, 16, v225
	v_mul_f32_e32 v72, v74, v72
	v_cvt_pk_bf16_f32 v72, v72, s0
	ds_write_b16 v172, v72 offset:35104
	v_and_b32_e32 v72, 0xffff0000, v225
	v_mul_f32_e32 v72, v74, v72
	v_cvt_pk_bf16_f32 v72, v72, s0
	ds_write_b16 v172, v72 offset:35248
	s_nop 0
	v_mov_b32_e32 v119, 0
	s_nop 0
	s_waitcnt lgkmcnt(9)
	v_lshlrev_b32_e32 v76, 16, v228
	v_and_b32_e32 v72, 0xffff0000, v228
	v_mul_f32_e32 v76, v74, v76
	v_mul_f32_e32 v72, v74, v72
	v_cvt_pk_bf16_f32 v76, v76, s0
	v_cvt_pk_bf16_f32 v72, v72, s0
	ds_write_b16 v171, v76 offset:35392
	ds_write_b16 v172, v72 offset:35536
	v_lshlrev_b32_e32 v72, 16, v229
	v_mul_f32_e32 v72, v74, v72
	v_cvt_pk_bf16_f32 v72, v72, s0
	ds_write_b16 v172, v72 offset:35680
	v_and_b32_e32 v72, 0xffff0000, v229
	v_mul_f32_e32 v72, v74, v72
	v_cvt_pk_bf16_f32 v72, v72, s0
	ds_write_b16 v172, v72 offset:35824
	s_nop 0
	s_nop 0
	s_waitcnt lgkmcnt(12)
	v_lshlrev_b32_e32 v76, 16, v232
	v_and_b32_e32 v72, 0xffff0000, v232
	v_mul_f32_e32 v76, v74, v76
	v_mul_f32_e32 v72, v74, v72
	v_cvt_pk_bf16_f32 v76, v76, s0
	v_cvt_pk_bf16_f32 v72, v72, s0
	ds_write_b16 v171, v76 offset:35968
	ds_write_b16 v172, v72 offset:36112
	v_lshlrev_b32_e32 v72, 16, v233
	v_mul_f32_e32 v72, v74, v72
	v_cvt_pk_bf16_f32 v72, v72, s0
	ds_write_b16 v172, v72 offset:36256
	v_and_b32_e32 v72, 0xffff0000, v233
	v_mul_f32_e32 v72, v74, v72
	v_cvt_pk_bf16_f32 v72, v72, s0
	ds_write_b16 v172, v72 offset:36400
	s_nop 0
	s_nop 0
	s_waitcnt lgkmcnt(15)
	v_lshlrev_b32_e32 v76, 16, v236
	v_and_b32_e32 v72, 0xffff0000, v236
	v_mul_f32_e32 v76, v74, v76
	v_mul_f32_e32 v72, v74, v72
	v_cvt_pk_bf16_f32 v76, v76, s0
	v_cvt_pk_bf16_f32 v72, v72, s0
	ds_write_b16 v171, v76 offset:36544
	ds_write_b16 v172, v72 offset:36688
	v_lshlrev_b32_e32 v72, 16, v237
	v_mul_f32_e32 v72, v74, v72
	v_cvt_pk_bf16_f32 v72, v72, s0
	ds_write_b16 v172, v72 offset:36832
	v_and_b32_e32 v72, 0xffff0000, v237
	v_mul_f32_e32 v72, v74, v72
	v_cvt_pk_bf16_f32 v72, v72, s0
	ds_write_b16 v172, v72 offset:36976
	s_nop 0
	s_nop 0
	s_waitcnt lgkmcnt(15)
	v_lshlrev_b32_e32 v76, 16, v240
	v_and_b32_e32 v72, 0xffff0000, v240
	v_mul_f32_e32 v76, v74, v76
	v_mul_f32_e32 v72, v74, v72
	v_cvt_pk_bf16_f32 v76, v76, s0
	v_cvt_pk_bf16_f32 v72, v72, s0
	ds_write_b16 v171, v76 offset:37120
	ds_write_b16 v172, v72 offset:37264
	v_lshlrev_b32_e32 v72, 16, v241
	v_mul_f32_e32 v72, v74, v72
	v_cvt_pk_bf16_f32 v72, v72, s0
	ds_write_b16 v172, v72 offset:37408
	v_and_b32_e32 v72, 0xffff0000, v241
	v_mul_f32_e32 v72, v74, v72
	v_cvt_pk_bf16_f32 v72, v72, s0
	ds_write_b16 v172, v72 offset:37552
	s_nop 0
	s_nop 0
	s_waitcnt lgkmcnt(15)
	v_lshlrev_b32_e32 v76, 16, v244
	v_and_b32_e32 v72, 0xffff0000, v244
	v_mul_f32_e32 v76, v74, v76
	v_mul_f32_e32 v72, v74, v72
	v_cvt_pk_bf16_f32 v76, v76, s0
	v_cvt_pk_bf16_f32 v72, v72, s0
	ds_write_b16 v171, v76 offset:37696
	ds_write_b16 v172, v72 offset:37840
	v_lshlrev_b32_e32 v72, 16, v245
	v_mul_f32_e32 v72, v74, v72
	v_cvt_pk_bf16_f32 v72, v72, s0
	ds_write_b16 v172, v72 offset:37984
	v_and_b32_e32 v72, 0xffff0000, v245
	v_mul_f32_e32 v72, v74, v72
	v_cvt_pk_bf16_f32 v72, v72, s0
	ds_write_b16 v172, v72 offset:38128
	s_nop 0
	s_nop 0
	s_waitcnt lgkmcnt(15)
	v_lshlrev_b32_e32 v76, 16, v248
	v_and_b32_e32 v72, 0xffff0000, v248
	v_mul_f32_e32 v76, v74, v76
	v_mul_f32_e32 v72, v74, v72
	v_cvt_pk_bf16_f32 v76, v76, s0
	v_cvt_pk_bf16_f32 v72, v72, s0
	ds_write_b16 v171, v76 offset:38272
	ds_write_b16 v172, v72 offset:38416
	v_lshlrev_b32_e32 v72, 16, v249
	v_mul_f32_e32 v72, v74, v72
	v_cvt_pk_bf16_f32 v72, v72, s0
	ds_write_b16 v172, v72 offset:38560
	v_and_b32_e32 v72, 0xffff0000, v249
	v_mul_f32_e32 v72, v74, v72
	v_cvt_pk_bf16_f32 v72, v72, s0
	ds_write_b16 v172, v72 offset:38704
	ds_read_b64 v[72:73], v75 offset:17464
	s_nop 0
	s_waitcnt lgkmcnt(0)
	v_lshlrev_b32_e32 v75, 16, v72
	v_and_b32_e32 v72, 0xffff0000, v72
	v_mul_f32_e32 v75, v74, v75
	v_mul_f32_e32 v72, v74, v72
	v_cvt_pk_bf16_f32 v75, v75, s0
	v_cvt_pk_bf16_f32 v72, v72, s0
	ds_write_b16 v171, v75 offset:38848
	ds_write_b16 v172, v72 offset:38992
	v_lshlrev_b32_e32 v72, 16, v73
	v_mul_f32_e32 v72, v74, v72
	v_cvt_pk_bf16_f32 v72, v72, s0
	ds_write_b16 v172, v72 offset:39136
	v_and_b32_e32 v72, 0xffff0000, v73
	v_mul_f32_e32 v72, v74, v72
	v_cvt_pk_bf16_f32 v72, v72, s0
	ds_write_b16 v172, v72 offset:39280
	s_waitcnt lgkmcnt(0)
	s_waitcnt lgkmcnt(0)
	s_barrier
	ds_read_b32 v224, v175
	ds_read_b32 v225, v176
	ds_read_b32 v226, v178
	ds_read_b32 v227, v179
	ds_read_b32 v228, v180
	ds_read_b32 v229, v181
	ds_read_b32 v230, v203
	ds_read_b32 v231, v204
	ds_read_b32 v232, v205
	ds_read_b32 v233, v206
	ds_read_b32 v234, v207
	ds_read_b32 v235, v211
	s_waitcnt lgkmcnt(8)
	ds_read_b32 v236, v174
	ds_read_b32 v237, v174 offset:4
	ds_read_b32 v238, v208
	ds_read_b32 v239, v160
	s_waitcnt lgkmcnt(4)
	ds_read_b128 v[72:75], v93 offset:17408
	ds_read_b128 v[76:79], v155
	ds_read_b128 v[84:87], v93 offset:17472
	s_waitcnt lgkmcnt(1)
	v_mfma_f32_16x16x32_bf16 v[88:91], v[72:75], v[76:79], 0
	ds_read_b128 v[218:221], v93 offset:17536
	ds_read_b128 v[80:83], v155 offset:64
	ds_read_b128 v[72:75], v155 offset:128
	s_waitcnt lgkmcnt(1)
	v_mfma_f32_16x16x32_bf16 v[84:87], v[84:87], v[80:83], v[88:91]
	s_nop 2
	ds_read_b128 v[88:91], v93 offset:17600
	s_waitcnt lgkmcnt(1)
	v_mfma_f32_16x16x32_bf16 v[218:221], v[218:221], v[72:75], v[84:87]
	s_nop 2
	ds_read_b128 v[84:87], v155 offset:192
	ds_read_b32 v92, v154
	s_waitcnt lgkmcnt(1)
	v_mfma_f32_16x16x32_bf16 v[88:91], v[88:91], v[84:87], v[218:221]
	s_and_saveexec_b64 s[6:7], s[52:53]
	s_cbranch_execnz .LBB0_605
	s_or_b64 exec, exec, s[6:7]
	s_nop 4
	v_mov_b32_e32 v88, 0
	s_and_saveexec_b64 s[6:7], s[54:55]
	s_cbranch_execnz .LBB0_606

; DI void xcd_barrier(const XcdBarrier& b) {
;   asm volatile("s_waitcnt vmcnt(0)" ::: "memory");
;   __syncthreads();
;   if (threadIdx.x == 0) {
;     unsigned* bar = b.bar;
;     __builtin_amdgcn_s_waitcnt(0);
;     unsigned nloc = b.st[0], nx = b.st[1];
;     if (nloc == 0u) { xcd_barrier_complete(bar, b.x, nloc, nx); b.st[0] = nloc; b.st[1] = nx; }
.LBB0_620:
	s_nop 0
	s_nop 0
	s_nop 0
	s_nop 0
	s_nop 0
	s_nop 0
	s_nop 0
	s_nop 0
	s_nop 0
	s_nop 0
	s_nop 0
	s_nop 0
	s_nop 0
	s_nop 0
	s_nop 0
	s_nop 0
	s_nop 0
	s_nop 0
	s_nop 0
	s_nop 0
	s_nop 0
	s_nop 0
	s_nop 0
	s_nop 0
	s_nop 0
	s_nop 0
	s_nop 0
	s_nop 0
	s_nop 0
	s_nop 0
	s_nop 0
	s_nop 0
	s_waitcnt vmcnt(0)
	s_barrier
	s_mov_b64 s[0:1], exec
	v_readlane_b32 s6, v252, 1
	v_readlane_b32 s7, v252, 2
	s_and_b64 s[6:7], s[0:1], s[6:7]
	s_mov_b64 exec, s[6:7]
	s_cbranch_execz .LBB0_672
	s_waitcnt vmcnt(0) expcnt(0) lgkmcnt(0)
	ds_read_b32 v2, v161
	ds_read_b32 v0, v161 offset:4
	s_waitcnt lgkmcnt(1)
	v_cmp_ne_u32_e32 vcc, 0, v2
	s_cbranch_vccnz .LBB0_636
	s_mov_b32 s2, 1
	s_branch .LBB0_624
